# e22: P10 staggered - odd 8-groups run gla_finish before their FNet GEMM unit, even groups after (on top of e18)
# speedup vs baseline: 1.0087x; 1.0087x over previous
.LBB0_1586:
	s_cmp_lt_i32 s88, 11
	s_cselect_b64 s[18:19], -1, 0
	s_and_b64 s[0:1], s[18:19], s[0:1]
	s_andn2_b64 vcc, exec, s[0:1]
	s_cbranch_vccnz .LBB0_1596
	s_bitcmp1_b32 s2, 3
	s_cbranch_scc0 .Le22_gemm
	s_cmpk_gt_u32 s57, 0xfff
	s_cbranch_scc1 .Le22_gemm
	s_cmpk_eq_u32 s99, 0x7772
	s_cbranch_scc1 .Le22_gemm
	s_movk_i32 s99, 0x7771
	v_mov_b32_e32 v131, 0
	s_branch .Le22_fin
.Le22_gemm:
	v_lshlrev_b32_e32 v1, 4, v0
	s_waitcnt vmcnt(0)
	v_and_b32_e32 v2, 32, v0
	v_bitop3_b32 v10, v1, v2, 48 bitop3:0x6c
	v_and_b32_e32 v11, 64, v0
	v_or_b32_e32 v1, v10, v11
	v_lshrrev_b32_e32 v2, 1, v1
	v_lshrrev_b32_e32 v1, 1, v0
	v_lshrrev_b32_e32 v4, 5, v0
	v_and_b32_e32 v1, 24, v1
	v_and_b32_e32 v4, 4, v4
	v_bfe_u32 v5, v0, 2, 2
	v_bfe_u32 v3, v0, 2, 4
	v_or3_b32 v4, v4, v5, v1
	v_lshrrev_b32_e32 v5, 3, v0
	v_and_or_b32 v6, v5, 48, v3
	v_and_or_b32 v5, v5, 32, v4
	v_mul_u32_u24_e32 v5, 0x1080, v5
	v_or_b32_e32 v5, v5, v2
	v_lshlrev_b32_e32 v132, 1, v5
	v_bfe_u32 v5, v0, 3, 25
	v_or_b32_e32 v5, 64, v5
	s_movk_i32 s0, 0x70
	v_and_or_b32 v3, v5, s0, v3
	s_movk_i32 s0, 0x60
	v_and_or_b32 v4, v5, s0, v4
	s_ashr_i32 s0, s2, 7
	v_readfirstlane_b32 s1, v0
	s_bfe_u32 s20, s2, 0x40003
	s_lshl_b32 s10, s0, 4
	s_lshl_b32 s12, s0, 3
	s_and_b32 s21, s2, 7
	s_lshr_b32 s9, s1, 6
	s_or_b32 s4, s20, s10
	s_or_b32 s5, s12, s21
	s_lshr_b32 s8, s1, 8
	s_lshl_b32 s14, s9, 10
	s_mul_hi_i32 s11, s4, 0x210000
	s_mul_i32 s13, s4, 0x210000
	s_mul_hi_i32 s4, s5, 0x210000
	s_mul_i32 s5, s5, 0x210000
	s_add_u32 s6, s92, s5
	s_addc_u32 s7, s93, s4
	v_mul_u32_u24_e32 v13, 0x1080, v3
	s_add_u32 s4, s6, 0x57600000
	v_or_b32_e32 v3, v13, v2
	s_addc_u32 s5, s7, 0
	s_add_i32 s22, s14, 0
	v_mul_u32_u24_e32 v12, 0x1080, v6
	v_lshlrev_b32_e32 v134, 1, v3
	v_mul_u32_u24_e32 v3, 0x1080, v4
	s_add_i32 m0, s22, 0x10000
	v_or_b32_e32 v6, v2, v12
	v_or_b32_e32 v2, v3, v2
	global_load_lds_dwordx4 v132, s[4:5]
	s_add_i32 m0, s22, 0x12000
	v_lshlrev_b32_e32 v136, 1, v2
	s_add_u32 s6, s6, 0x57708000
	global_load_lds_dwordx4 v136, s[4:5]
	s_addc_u32 s7, s7, 0
	s_add_i32 m0, s22, 0x14000
	v_lshlrev_b32_e32 v130, 1, v6
	global_load_lds_dwordx4 v132, s[6:7]
	s_add_i32 m0, s22, 0x16000
	s_add_u32 s13, s92, s13
	s_addc_u32 s11, s93, s11
	global_load_lds_dwordx4 v136, s[6:7]
	s_add_u32 s6, s13, 0x11200000
	s_addc_u32 s7, s11, 0
	s_add_i32 s23, s22, 0x2000
	s_mov_b32 m0, s22
	s_add_u32 s16, s13, 0x11308000
	global_load_lds_dwordx4 v130, s[6:7]
	s_mov_b32 m0, s23
	s_addc_u32 s17, s11, 0
	s_add_i32 s24, s22, 0x4000
	global_load_lds_dwordx4 v134, s[6:7]
	s_mov_b32 m0, s24
	s_add_i32 s25, s22, 0x6000
	global_load_lds_dwordx4 v130, s[16:17]
	s_mov_b32 m0, s25
	v_mov_b32_e32 v133, 0
	global_load_lds_dwordx4 v134, s[16:17]
	v_mov_b32_e32 v137, v133
	v_mov_b32_e32 v131, v133
	v_mov_b32_e32 v135, v133
	v_lshl_add_u64 v[8:9], s[4:5], 0, v[132:133]
	v_lshl_add_u64 v[6:7], s[4:5], 0, v[136:137]
	v_lshl_add_u64 v[4:5], s[6:7], 0, v[130:131]
	s_cmp_lg_u32 s8, 1
	v_lshl_add_u64 v[2:3], s[6:7], 0, v[134:135]
	s_cbranch_scc1 .LBB0_1589
	s_barrier

.LBB0_1593:
	s_add_u32 s4, s92, 0x4ec00000
	s_addc_u32 s5, s93, 0
	s_ashr_i32 s1, s0, 31
	v_lshl_add_u32 v130, s20, 8, v142
	v_mov_b32_e32 v131, 0
	s_lshl_b64 s[0:1], s[0:1], 24
	v_lshlrev_b64 v[132:133], 12, v[130:131]
	v_lshl_or_b32 v1, s21, 8, v1
	v_lshl_add_u64 v[132:133], v[132:133], 0, s[0:1]
	s_mov_b32 s0, 0x3a3504f3
	v_or_b32_e32 v1, s26, v1
	v_pk_mul_f32 v[126:127], v[126:127], s[0:1] op_sel_hi:[1,0]
	v_pk_mul_f32 v[122:123], v[122:123], s[0:1] op_sel_hi:[1,0]
	v_pk_mul_f32 v[128:129], v[128:129], s[0:1] op_sel_hi:[1,0]
	v_pk_mul_f32 v[134:135], v[124:125], s[0:1] op_sel_hi:[1,0]
	v_cvt_pk_bf16_f32 v124, v126, v127
	v_cvt_pk_bf16_f32 v125, v128, v129
	v_cvt_pk_bf16_f32 v126, v122, v123
	v_lshl_add_u64 v[122:123], s[4:5], 0, v[132:133]
	v_lshlrev_b32_e32 v130, 1, v1
	v_lshl_add_u64 v[122:123], v[122:123], 0, v[130:131]
	v_cvt_pk_bf16_f32 v127, v134, v135
	global_store_dwordx4 v[122:123], v[124:127], off
	v_pk_mul_f32 v[120:121], v[120:121], s[0:1] op_sel_hi:[1,0]
	v_pk_mul_f32 v[118:119], v[118:119], s[0:1] op_sel_hi:[1,0]
	v_pk_mul_f32 v[124:125], v[112:113], s[0:1] op_sel_hi:[1,0]
	v_pk_mul_f32 v[112:113], v[110:111], s[0:1] op_sel_hi:[1,0]
	v_cvt_pk_bf16_f32 v110, v118, v119
	v_cvt_pk_bf16_f32 v111, v120, v121
	v_pk_mul_f32 v[114:115], v[114:115], s[0:1] op_sel_hi:[1,0]
	v_cvt_pk_bf16_f32 v112, v112, v113
	v_cvt_pk_bf16_f32 v113, v124, v125
	global_store_dwordx4 v[122:123], v[110:113], off offset:256
	v_pk_mul_f32 v[104:105], v[104:105], s[0:1] op_sel_hi:[1,0]
	v_pk_mul_f32 v[102:103], v[102:103], s[0:1] op_sel_hi:[1,0]
	v_or_b32_e32 v110, 0x10000, v132
	v_mov_b32_e32 v111, v133
	v_lshl_add_u64 v[110:111], s[4:5], 0, v[110:111]
	v_pk_mul_f32 v[112:113], v[116:117], s[0:1] op_sel_hi:[1,0]
	v_pk_mul_f32 v[116:117], v[108:109], s[0:1] op_sel_hi:[1,0]
	v_pk_mul_f32 v[108:109], v[106:107], s[0:1] op_sel_hi:[1,0]
	v_cvt_pk_bf16_f32 v106, v114, v115
	v_cvt_pk_bf16_f32 v107, v112, v113
	v_lshl_add_u64 v[110:111], v[110:111], 0, v[130:131]
	v_cvt_pk_bf16_f32 v108, v108, v109
	v_cvt_pk_bf16_f32 v109, v116, v117
	global_store_dwordx4 v[110:111], v[106:109], off
	v_pk_mul_f32 v[98:99], v[98:99], s[0:1] op_sel_hi:[1,0]
	v_pk_mul_f32 v[88:89], v[88:89], s[0:1] op_sel_hi:[1,0]
	v_pk_mul_f32 v[106:107], v[96:97], s[0:1] op_sel_hi:[1,0]
	v_pk_mul_f32 v[96:97], v[94:95], s[0:1] op_sel_hi:[1,0]
	v_cvt_pk_bf16_f32 v94, v102, v103
	v_cvt_pk_bf16_f32 v95, v104, v105
	v_pk_mul_f32 v[86:87], v[86:87], s[0:1] op_sel_hi:[1,0]
	v_cvt_pk_bf16_f32 v96, v96, v97
	v_cvt_pk_bf16_f32 v97, v106, v107
	global_store_dwordx4 v[110:111], v[94:97], off offset:256
	v_pk_mul_f32 v[72:73], v[72:73], s[0:1] op_sel_hi:[1,0]
	v_pk_mul_f32 v[70:71], v[70:71], s[0:1] op_sel_hi:[1,0]
	v_or_b32_e32 v94, 0x20000, v132
	v_mov_b32_e32 v95, v133
	v_lshl_add_u64 v[94:95], s[4:5], 0, v[94:95]
	v_pk_mul_f32 v[96:97], v[100:101], s[0:1] op_sel_hi:[1,0]
	v_pk_mul_f32 v[100:101], v[92:93], s[0:1] op_sel_hi:[1,0]
	v_pk_mul_f32 v[92:93], v[90:91], s[0:1] op_sel_hi:[1,0]
	v_cvt_pk_bf16_f32 v90, v98, v99
	v_cvt_pk_bf16_f32 v91, v96, v97
	v_lshl_add_u64 v[94:95], v[94:95], 0, v[130:131]
	v_cvt_pk_bf16_f32 v92, v92, v93
	v_cvt_pk_bf16_f32 v93, v100, v101
	global_store_dwordx4 v[94:95], v[90:93], off
	v_or_b32_e32 v132, 0x30000, v132
	v_pk_mul_f32 v[64:65], v[64:65], s[0:1] op_sel_hi:[1,0]
	v_pk_mul_f32 v[90:91], v[80:81], s[0:1] op_sel_hi:[1,0]
	v_pk_mul_f32 v[80:81], v[78:79], s[0:1] op_sel_hi:[1,0]
	v_cvt_pk_bf16_f32 v78, v86, v87
	v_cvt_pk_bf16_f32 v79, v88, v89
	v_pk_mul_f32 v[62:63], v[62:63], s[0:1] op_sel_hi:[1,0]
	v_cvt_pk_bf16_f32 v80, v80, v81
	v_cvt_pk_bf16_f32 v81, v90, v91
	global_store_dwordx4 v[94:95], v[78:81], off offset:256
	s_cmpk_gt_u32 s57, 0xfff
	s_nop 0
	v_pk_mul_f32 v[78:79], v[84:85], s[0:1] op_sel_hi:[1,0]
	v_pk_mul_f32 v[80:81], v[82:83], s[0:1] op_sel_hi:[1,0]
	v_pk_mul_f32 v[82:83], v[76:77], s[0:1] op_sel_hi:[1,0]
	v_pk_mul_f32 v[76:77], v[74:75], s[0:1] op_sel_hi:[1,0]
	v_cvt_pk_bf16_f32 v74, v80, v81
	v_cvt_pk_bf16_f32 v75, v78, v79
	v_lshl_add_u64 v[78:79], s[4:5], 0, v[132:133]
	v_lshl_add_u64 v[78:79], v[78:79], 0, v[130:131]
	v_cvt_pk_bf16_f32 v76, v76, v77
	v_cvt_pk_bf16_f32 v77, v82, v83
	global_store_dwordx4 v[78:79], v[74:77], off
	s_mov_b64 s[4:5], 0x80000
	s_nop 0
	v_pk_mul_f32 v[74:75], v[68:69], s[0:1] op_sel_hi:[1,0]
	v_pk_mul_f32 v[68:69], v[66:67], s[0:1] op_sel_hi:[1,0]
	v_cvt_pk_bf16_f32 v66, v70, v71
	v_cvt_pk_bf16_f32 v67, v72, v73
	s_nop 0
	v_cvt_pk_bf16_f32 v68, v68, v69
	v_cvt_pk_bf16_f32 v69, v74, v75
	global_store_dwordx4 v[78:79], v[66:69], off offset:256
	s_nop 1
	v_pk_mul_f32 v[66:67], v[60:61], s[0:1] op_sel_hi:[1,0]
	v_pk_mul_f32 v[60:61], v[58:59], s[0:1] op_sel_hi:[1,0]
	s_mov_b32 s1, 0x80000
	v_cvt_pk_bf16_f32 v58, v62, v63
	v_cvt_pk_bf16_f32 v59, v64, v65
	v_add_co_u32_e32 v64, vcc, s1, v122
	v_cvt_pk_bf16_f32 v60, v60, v61
	v_cvt_pk_bf16_f32 v61, v66, v67
	v_lshl_add_u64 v[62:63], v[122:123], 0, s[4:5]
	s_nop 0
	v_addc_co_u32_e32 v65, vcc, 0, v123, vcc
	global_store_dwordx4 v[64:65], v[58:61], off
	v_pk_mul_f32 v[56:57], v[56:57], s[0:1] op_sel_hi:[1,0]
	v_pk_mul_f32 v[54:55], v[54:55], s[0:1] op_sel_hi:[1,0]
	v_pk_mul_f32 v[58:59], v[48:49], s[0:1] op_sel_hi:[1,0]
	v_pk_mul_f32 v[48:49], v[46:47], s[0:1] op_sel_hi:[1,0]
	v_cvt_pk_bf16_f32 v46, v54, v55
	v_cvt_pk_bf16_f32 v47, v56, v57
	s_mov_b64 s[4:5], 0x90000
	v_cvt_pk_bf16_f32 v48, v48, v49
	v_cvt_pk_bf16_f32 v49, v58, v59
	global_store_dwordx4 v[62:63], v[46:49], off offset:256
	s_nop 1
	v_pk_mul_f32 v[46:47], v[52:53], s[0:1] op_sel_hi:[1,0]
	v_pk_mul_f32 v[48:49], v[50:51], s[0:1] op_sel_hi:[1,0]
	v_pk_mul_f32 v[50:51], v[44:45], s[0:1] op_sel_hi:[1,0]
	v_pk_mul_f32 v[44:45], v[42:43], s[0:1] op_sel_hi:[1,0]
	s_mov_b32 s1, 0x90000
	v_cvt_pk_bf16_f32 v42, v48, v49
	v_add_co_u32_e32 v48, vcc, s1, v122
	v_cvt_pk_bf16_f32 v43, v46, v47
	v_cvt_pk_bf16_f32 v44, v44, v45
	v_cvt_pk_bf16_f32 v45, v50, v51
	v_lshl_add_u64 v[46:47], v[122:123], 0, s[4:5]
	s_nop 0
	v_addc_co_u32_e32 v49, vcc, 0, v123, vcc
	global_store_dwordx4 v[48:49], v[42:45], off
	v_pk_mul_f32 v[40:41], v[40:41], s[0:1] op_sel_hi:[1,0]
	v_pk_mul_f32 v[38:39], v[38:39], s[0:1] op_sel_hi:[1,0]
	v_pk_mul_f32 v[42:43], v[32:33], s[0:1] op_sel_hi:[1,0]
	v_pk_mul_f32 v[32:33], v[30:31], s[0:1] op_sel_hi:[1,0]
	v_cvt_pk_bf16_f32 v30, v38, v39
	v_cvt_pk_bf16_f32 v31, v40, v41
	s_mov_b64 s[4:5], 0xa0000
	v_cvt_pk_bf16_f32 v32, v32, v33
	v_cvt_pk_bf16_f32 v33, v42, v43
	global_store_dwordx4 v[46:47], v[30:33], off offset:256
	s_nop 1
	v_pk_mul_f32 v[30:31], v[36:37], s[0:1] op_sel_hi:[1,0]
	v_pk_mul_f32 v[32:33], v[34:35], s[0:1] op_sel_hi:[1,0]
	v_pk_mul_f32 v[34:35], v[28:29], s[0:1] op_sel_hi:[1,0]
	v_pk_mul_f32 v[28:29], v[26:27], s[0:1] op_sel_hi:[1,0]
	s_mov_b32 s1, 0xa0000
	v_cvt_pk_bf16_f32 v26, v32, v33
	v_add_co_u32_e32 v32, vcc, s1, v122
	v_cvt_pk_bf16_f32 v27, v30, v31
	v_cvt_pk_bf16_f32 v28, v28, v29
	v_cvt_pk_bf16_f32 v29, v34, v35
	v_lshl_add_u64 v[30:31], v[122:123], 0, s[4:5]
	s_nop 0
	v_addc_co_u32_e32 v33, vcc, 0, v123, vcc
	global_store_dwordx4 v[32:33], v[26:29], off
	v_pk_mul_f32 v[24:25], v[24:25], s[0:1] op_sel_hi:[1,0]
	v_pk_mul_f32 v[22:23], v[22:23], s[0:1] op_sel_hi:[1,0]
	v_pk_mul_f32 v[26:27], v[16:17], s[0:1] op_sel_hi:[1,0]
	v_pk_mul_f32 v[16:17], v[14:15], s[0:1] op_sel_hi:[1,0]
	v_cvt_pk_bf16_f32 v14, v22, v23
	v_cvt_pk_bf16_f32 v15, v24, v25
	s_mov_b64 s[4:5], 0xb0000
	v_cvt_pk_bf16_f32 v16, v16, v17
	v_cvt_pk_bf16_f32 v17, v26, v27
	global_store_dwordx4 v[30:31], v[14:17], off offset:256
	s_nop 1
	v_pk_mul_f32 v[14:15], v[20:21], s[0:1] op_sel_hi:[1,0]
	v_pk_mul_f32 v[16:17], v[18:19], s[0:1] op_sel_hi:[1,0]
	v_pk_mul_f32 v[18:19], v[12:13], s[0:1] op_sel_hi:[1,0]
	v_pk_mul_f32 v[12:13], v[10:11], s[0:1] op_sel_hi:[1,0]
	s_mov_b32 s1, 0xb0000
	v_cvt_pk_bf16_f32 v10, v16, v17
	v_add_co_u32_e32 v16, vcc, s1, v122
	v_cvt_pk_bf16_f32 v11, v14, v15
	v_cvt_pk_bf16_f32 v12, v12, v13
	v_cvt_pk_bf16_f32 v13, v18, v19
	v_lshl_add_u64 v[14:15], v[122:123], 0, s[4:5]
	s_nop 0
	v_addc_co_u32_e32 v17, vcc, 0, v123, vcc
	global_store_dwordx4 v[16:17], v[10:13], off
	v_pk_mul_f32 v[8:9], v[8:9], s[0:1] op_sel_hi:[1,0]
	v_pk_mul_f32 v[6:7], v[6:7], s[0:1] op_sel_hi:[1,0]
	v_pk_mul_f32 v[10:11], v[4:5], s[0:1] op_sel_hi:[1,0]
	v_pk_mul_f32 v[4:5], v[2:3], s[0:1] op_sel_hi:[1,0]
	v_cvt_pk_bf16_f32 v2, v6, v7
	v_cvt_pk_bf16_f32 v3, v8, v9
	s_nop 0
	v_cvt_pk_bf16_f32 v4, v4, v5
	v_cvt_pk_bf16_f32 v5, v10, v11
	global_store_dwordx4 v[14:15], v[2:5], off offset:256
	s_waitcnt vmcnt(0)
	s_barrier
	s_cbranch_scc1 .LBB0_1596
	s_cmpk_eq_u32 s99, 0x7772
	s_cbranch_scc0 .Le22_fin
	s_mov_b32 s99, 0
	v_readlane_b32 s16, v254, 27
	v_readlane_b32 s21, v254, 28
	v_readlane_b32 s23, v254, 29
	s_nop 4
	s_branch .LBB0_1596
.Le22_fin:
	v_lshlrev_b32_e32 v1, 5, v162
	global_load_dwordx4 v[2:5], v1, s[80:81] offset:16 nt
	global_load_dwordx4 v[6:9], v1, s[80:81] nt
	v_mbcnt_lo_u32_b32 v1, -1, 0
	v_mbcnt_hi_u32_b32 v10, -1, v1
	v_and_b32_e32 v1, 64, v10
	v_add_u32_e32 v11, 64, v1
	v_xor_b32_e32 v1, 1, v10
	v_cmp_lt_i32_e32 vcc, v1, v11
	v_xor_b32_e32 v12, 2, v10
	s_add_u32 s20, s92, 0x21600000
	v_cndmask_b32_e32 v1, v10, v1, vcc
	v_cmp_lt_i32_e32 vcc, v12, v11
	s_addc_u32 s21, s93, 0
	s_add_u32 s22, s92, 0x27900000
	v_cndmask_b32_e32 v12, v10, v12, vcc
	v_lshlrev_b32_e32 v51, 2, v12
	v_xor_b32_e32 v12, 4, v10
	v_cmp_lt_i32_e32 vcc, v12, v11
	s_addc_u32 s23, s93, 0
	s_add_u32 s24, s92, 0x50c00000
	v_cndmask_b32_e32 v12, v10, v12, vcc
	v_lshlrev_b32_e32 v64, 2, v12
	v_xor_b32_e32 v12, 8, v10
	v_cmp_lt_i32_e32 vcc, v12, v11
	s_addc_u32 s25, s93, 0
	s_add_u32 s26, s92, 0x19200000
	v_cndmask_b32_e32 v12, v10, v12, vcc
	v_lshlrev_b32_e32 v65, 2, v12
	v_xor_b32_e32 v12, 16, v10
	v_cmp_lt_i32_e32 vcc, v12, v11
	s_addc_u32 s27, s93, 0
	v_lshlrev_b32_e32 v130, 4, v162
	v_cndmask_b32_e32 v12, v10, v12, vcc
	v_lshlrev_b32_e32 v66, 2, v12
	v_xor_b32_e32 v12, 32, v10
	v_cmp_lt_i32_e32 vcc, v12, v11
	s_add_u32 s30, s92, 0x38100000
	s_mov_b64 s[0:1], 0x2fd00000
	v_cndmask_b32_e32 v10, v10, v12, vcc
	v_lshlrev_b32_e32 v67, 2, v10
	v_lshl_add_u64 v[10:11], s[92:93], 0, v[130:131]
	s_addc_u32 s31, s93, 0
	s_lshl_b32 s34, s2, 6
	v_lshlrev_b32_e32 v50, 3, v162
	v_lshlrev_b32_e32 v1, 2, v1
	v_lshl_add_u64 v[52:53], v[10:11], 0, s[0:1]
	s_movk_i32 s35, 0x1000
	v_mov_b32_e32 v68, 0x358637bd
	s_mov_b32 s36, 0xf800000
	v_mov_b32_e32 v69, 0x260
	s_mov_b32 s37, s33
.LBB0_1595:
	s_add_i32 s0, s34, s37
	s_ashr_i32 s1, s0, 31
	s_lshr_b32 s1, s1, 19
	s_add_i32 s1, s0, s1
	s_ashr_i32 s4, s1, 13
	s_and_b32 s1, s1, 0xffffe000
	s_sub_i32 s0, s0, s1
	s_mul_hi_i32 s5, s4, 0x2100
	s_mulk_i32 s4, 0x2100
	s_ashr_i32 s1, s0, 31
	s_add_u32 s0, s4, s0
	s_addc_u32 s1, s5, s1
	s_mul_hi_u32 s4, s0, 0xc00
	s_mul_i32 s5, s0, 0xc00
	s_mul_i32 s6, s1, 0xc00
	s_lshl_b64 s[0:1], s[0:1], 13
	s_add_i32 s4, s4, s6
	v_lshl_add_u64 v[12:13], v[52:53], 0, s[0:1]
	v_or_b32_e32 v10, s5, v50
	v_mov_b32_e32 v11, s4
	v_add_co_u32_e32 v36, vcc, s35, v12
	v_lshlrev_b64 v[34:35], 1, v[10:11]
	s_nop 0
	v_addc_co_u32_e32 v37, vcc, 0, v13, vcc
	global_load_dwordx4 v[30:33], v[12:13], off nt
	global_load_dwordx4 v[26:29], v[12:13], off offset:1024 nt
	global_load_dwordx4 v[22:25], v[12:13], off offset:2048 nt
	global_load_dwordx4 v[18:21], v[12:13], off offset:3072 nt
	global_load_dwordx4 v[14:17], v[36:37], off nt
	s_nop 0
	global_load_dwordx4 v[10:13], v[36:37], off offset:1024 nt
	v_lshl_add_u64 v[36:37], s[20:21], 0, v[34:35]
	v_lshl_add_u64 v[38:39], s[22:23], 0, v[34:35]
	v_lshl_add_u64 v[40:41], s[24:25], 0, v[34:35]
	v_lshl_add_u64 v[42:43], s[26:27], 0, v[34:35]
	global_load_dwordx4 v[56:59], v[36:37], off nt
	global_load_dwordx4 v[60:63], v[36:37], off offset:2048 nt
	global_load_dwordx4 v[118:121], v[40:41], off nt
	global_load_dwordx4 v[122:125], v[40:41], off offset:2048 nt
	global_load_dwordx4 v[126:129], v[38:39], off nt
	global_load_dwordx4 v[132:135], v[36:37], off offset:3072 nt
	global_load_dwordx4 v[136:139], v[38:39], off offset:2048 nt
	global_load_dwordx4 v[140:143], v[38:39], off offset:3072 nt
	global_load_dwordx4 v[144:147], v[42:43], off nt
	global_load_dwordx4 v[148:151], v[40:41], off offset:3072 nt
	global_load_dwordx4 v[152:155], v[42:43], off offset:2048 nt
	global_load_dwordx4 v[156:159], v[42:43], off offset:3072 nt
	v_add_co_u32_e32 v36, vcc, s35, v36
	s_add_u32 s28, s30, s0
	s_nop 0
	v_addc_co_u32_e32 v37, vcc, 0, v37, vcc
	v_add_co_u32_e32 v38, vcc, s35, v38
	v_lshlrev_b32_e32 v130, 1, v50
	s_nop 0
	v_addc_co_u32_e32 v39, vcc, 0, v39, vcc
	v_add_co_u32_e32 v72, vcc, s35, v40
	s_addc_u32 s29, s31, s1
	s_nop 0
	v_addc_co_u32_e32 v73, vcc, 0, v41, vcc
	v_add_co_u32_e32 v74, vcc, s35, v42
	v_or_b32_e32 v34, 0x400, v34
	v_lshl_add_u64 v[44:45], s[28:29], 0, v[130:131]
	v_addc_co_u32_e32 v75, vcc, 0, v43, vcc
	v_lshl_add_u64 v[46:47], s[20:21], 0, v[34:35]
	v_lshl_add_u64 v[48:49], s[22:23], 0, v[34:35]
	v_lshl_add_u64 v[70:71], s[24:25], 0, v[34:35]
	v_lshl_add_u64 v[34:35], s[26:27], 0, v[34:35]
	v_add_co_u32_e32 v54, vcc, s35, v44
	s_add_i32 s0, s37, 8
	s_nop 0
	v_addc_co_u32_e32 v55, vcc, 0, v45, vcc
	global_load_dwordx4 v[164:167], v[46:47], off nt
	global_load_dwordx4 v[168:171], v[48:49], off nt
	global_load_dwordx4 v[172:175], v[70:71], off nt
	global_load_dwordx4 v[176:179], v[34:35], off nt
	global_load_dwordx4 v[180:183], v[36:37], off nt
	s_nop 0
	global_load_dwordx4 v[34:37], v[36:37], off offset:1024 nt
	s_nop 0
	global_load_dwordx4 v[184:187], v[38:39], off nt
	s_nop 0
	global_load_dwordx4 v[38:41], v[38:39], off offset:1024 nt
	s_nop 0
	global_load_dwordx4 v[188:191], v[72:73], off nt
	global_load_dwordx4 v[42:45], v[72:73], off offset:1024 nt
	global_load_dwordx4 v[192:195], v[74:75], off nt
	global_load_dwordx4 v[46:49], v[74:75], off offset:1024 nt
	s_cmp_lt_u32 s37, 56
	s_mov_b32 s37, s0
	s_waitcnt vmcnt(0)
	v_lshlrev_b32_e32 v160, 16, v62
	v_and_b32_e32 v161, 0xffff0000, v62
	v_lshlrev_b32_e32 v110, 16, v30
	v_and_b32_e32 v111, 0xffff0000, v30
	v_lshlrev_b32_e32 v78, 16, v14
	v_and_b32_e32 v79, 0xffff0000, v14
	v_lshlrev_b32_e32 v80, 16, v15
	v_and_b32_e32 v81, 0xffff0000, v15
	v_lshlrev_b32_e32 v82, 16, v16
	v_and_b32_e32 v83, 0xffff0000, v16
	v_lshlrev_b32_e32 v84, 16, v17
	v_and_b32_e32 v85, 0xffff0000, v17
	v_lshlrev_b32_e32 v70, 16, v10
	v_and_b32_e32 v71, 0xffff0000, v10
	v_lshlrev_b32_e32 v72, 16, v11
	v_and_b32_e32 v73, 0xffff0000, v11
	v_lshlrev_b32_e32 v74, 16, v12
	v_and_b32_e32 v75, 0xffff0000, v12
	v_lshlrev_b32_e32 v76, 16, v13
	v_and_b32_e32 v77, 0xffff0000, v13
	v_lshlrev_b32_e32 v10, 16, v56
	v_and_b32_e32 v11, 0xffff0000, v56
	v_lshlrev_b32_e32 v12, 16, v126
	v_and_b32_e32 v13, 0xffff0000, v126
	v_lshlrev_b32_e32 v14, 16, v118
	v_and_b32_e32 v15, 0xffff0000, v118
	v_lshlrev_b32_e32 v16, 16, v144
	v_and_b32_e32 v17, 0xffff0000, v144
	v_lshlrev_b32_e32 v112, 16, v31
	v_and_b32_e32 v113, 0xffff0000, v31
	v_lshlrev_b32_e32 v114, 16, v32
	v_and_b32_e32 v115, 0xffff0000, v32
	v_lshlrev_b32_e32 v116, 16, v33
	v_and_b32_e32 v117, 0xffff0000, v33
	v_lshlrev_b32_e32 v102, 16, v26
	v_and_b32_e32 v103, 0xffff0000, v26
	v_lshlrev_b32_e32 v104, 16, v27
	v_and_b32_e32 v105, 0xffff0000, v27
	v_lshlrev_b32_e32 v106, 16, v28
	v_and_b32_e32 v107, 0xffff0000, v28
	v_lshlrev_b32_e32 v108, 16, v29
	v_and_b32_e32 v109, 0xffff0000, v29
	v_lshlrev_b32_e32 v94, 16, v22
	v_and_b32_e32 v95, 0xffff0000, v22
	v_lshlrev_b32_e32 v96, 16, v23
	v_and_b32_e32 v97, 0xffff0000, v23
	v_lshlrev_b32_e32 v98, 16, v24
	v_and_b32_e32 v99, 0xffff0000, v24
	v_lshlrev_b32_e32 v100, 16, v25
	v_and_b32_e32 v101, 0xffff0000, v25
	v_lshlrev_b32_e32 v86, 16, v18
	v_and_b32_e32 v87, 0xffff0000, v18
	v_lshlrev_b32_e32 v88, 16, v19
	v_and_b32_e32 v89, 0xffff0000, v19
	v_lshlrev_b32_e32 v90, 16, v20
	v_and_b32_e32 v91, 0xffff0000, v20
	v_lshlrev_b32_e32 v92, 16, v21
	v_and_b32_e32 v93, 0xffff0000, v21
	v_lshlrev_b32_e32 v18, 16, v57
	v_and_b32_e32 v19, 0xffff0000, v57
	v_lshlrev_b32_e32 v20, 16, v127
	v_and_b32_e32 v21, 0xffff0000, v127
	v_lshlrev_b32_e32 v22, 16, v119
	v_and_b32_e32 v23, 0xffff0000, v119
	v_lshlrev_b32_e32 v24, 16, v145
	v_and_b32_e32 v25, 0xffff0000, v145
	v_lshlrev_b32_e32 v26, 16, v58
	v_and_b32_e32 v27, 0xffff0000, v58
	v_lshlrev_b32_e32 v28, 16, v128
	v_and_b32_e32 v29, 0xffff0000, v128
	v_lshlrev_b32_e32 v30, 16, v120
	v_and_b32_e32 v31, 0xffff0000, v120
	v_lshlrev_b32_e32 v32, 16, v146
	v_and_b32_e32 v33, 0xffff0000, v146
	v_lshlrev_b32_e32 v56, 16, v59
	v_and_b32_e32 v57, 0xffff0000, v59
	v_lshlrev_b32_e32 v58, 16, v129
	v_and_b32_e32 v59, 0xffff0000, v129
	v_lshlrev_b32_e32 v118, 16, v121
	v_and_b32_e32 v119, 0xffff0000, v121
	v_lshlrev_b32_e32 v120, 16, v147
	v_and_b32_e32 v121, 0xffff0000, v147
	v_lshlrev_b32_e32 v126, 16, v60
	v_and_b32_e32 v127, 0xffff0000, v60
	v_lshlrev_b32_e32 v128, 16, v136
	v_and_b32_e32 v129, 0xffff0000, v136
	v_lshlrev_b32_e32 v144, 16, v122
	v_and_b32_e32 v145, 0xffff0000, v122
	v_lshlrev_b32_e32 v146, 16, v152
	v_and_b32_e32 v147, 0xffff0000, v152
	v_lshlrev_b32_e32 v60, 16, v61
	v_and_b32_e32 v61, 0xffff0000, v61
	v_lshlrev_b32_e32 v136, 16, v137
	v_and_b32_e32 v137, 0xffff0000, v137
	v_lshlrev_b32_e32 v122, 16, v123
	v_and_b32_e32 v123, 0xffff0000, v123
	v_lshlrev_b32_e32 v152, 16, v153
	v_and_b32_e32 v153, 0xffff0000, v153
	v_lshlrev_b32_e32 v196, 16, v138
	v_and_b32_e32 v197, 0xffff0000, v138
	v_lshlrev_b32_e32 v198, 16, v124
	v_and_b32_e32 v199, 0xffff0000, v124
	v_lshlrev_b32_e32 v200, 16, v154
	v_and_b32_e32 v201, 0xffff0000, v154
	v_lshlrev_b32_e32 v62, 16, v63
	v_and_b32_e32 v63, 0xffff0000, v63
	v_lshlrev_b32_e32 v138, 16, v139
	v_and_b32_e32 v139, 0xffff0000, v139
	v_lshlrev_b32_e32 v124, 16, v125
	v_and_b32_e32 v125, 0xffff0000, v125
	v_lshlrev_b32_e32 v154, 16, v155
	v_and_b32_e32 v155, 0xffff0000, v155
	v_lshlrev_b32_e32 v202, 16, v132
	v_and_b32_e32 v203, 0xffff0000, v132
	v_lshlrev_b32_e32 v204, 16, v140
	v_and_b32_e32 v205, 0xffff0000, v140
	v_lshlrev_b32_e32 v206, 16, v148
	v_and_b32_e32 v207, 0xffff0000, v148
	v_lshlrev_b32_e32 v208, 16, v156
	v_and_b32_e32 v209, 0xffff0000, v156
	v_lshlrev_b32_e32 v132, 16, v133
	v_and_b32_e32 v133, 0xffff0000, v133
	v_lshlrev_b32_e32 v140, 16, v141
	v_and_b32_e32 v141, 0xffff0000, v141
	v_lshlrev_b32_e32 v148, 16, v149
	v_and_b32_e32 v149, 0xffff0000, v149
	v_lshlrev_b32_e32 v156, 16, v157
	v_and_b32_e32 v157, 0xffff0000, v157
	v_lshlrev_b32_e32 v210, 16, v134
	v_and_b32_e32 v211, 0xffff0000, v134
	v_lshlrev_b32_e32 v212, 16, v142
	v_and_b32_e32 v213, 0xffff0000, v142
	v_lshlrev_b32_e32 v214, 16, v150
	v_and_b32_e32 v215, 0xffff0000, v150
	v_lshlrev_b32_e32 v216, 16, v158
	v_and_b32_e32 v217, 0xffff0000, v158
	v_lshlrev_b32_e32 v134, 16, v135
	v_and_b32_e32 v135, 0xffff0000, v135
	v_lshlrev_b32_e32 v142, 16, v143
	v_and_b32_e32 v143, 0xffff0000, v143
	v_lshlrev_b32_e32 v150, 16, v151
	v_and_b32_e32 v151, 0xffff0000, v151
	v_lshlrev_b32_e32 v158, 16, v159
	v_and_b32_e32 v159, 0xffff0000, v159
	v_pk_add_f32 v[10:11], v[10:11], v[12:13]
	v_pk_add_f32 v[12:13], v[14:15], v[16:17]
	v_pk_add_f32 v[14:15], v[18:19], v[20:21]
	v_pk_add_f32 v[16:17], v[22:23], v[24:25]
	v_pk_add_f32 v[18:19], v[26:27], v[28:29]
	v_pk_add_f32 v[20:21], v[30:31], v[32:33]
	v_pk_add_f32 v[22:23], v[56:57], v[58:59]
	v_pk_add_f32 v[24:25], v[118:119], v[120:121]
	v_lshlrev_b32_e32 v26, 16, v164
	v_and_b32_e32 v27, 0xffff0000, v164
	v_lshlrev_b32_e32 v28, 16, v168
	v_and_b32_e32 v29, 0xffff0000, v168
	v_lshlrev_b32_e32 v30, 16, v172
	v_and_b32_e32 v31, 0xffff0000, v172
	v_lshlrev_b32_e32 v32, 16, v176
	v_and_b32_e32 v33, 0xffff0000, v176
	v_lshlrev_b32_e32 v56, 16, v165
	v_and_b32_e32 v57, 0xffff0000, v165
	v_lshlrev_b32_e32 v58, 16, v169
	v_and_b32_e32 v59, 0xffff0000, v169
	v_lshlrev_b32_e32 v118, 16, v173
	v_and_b32_e32 v119, 0xffff0000, v173
	v_lshlrev_b32_e32 v120, 16, v177
	v_and_b32_e32 v121, 0xffff0000, v177
	v_lshlrev_b32_e32 v164, 16, v166
	v_and_b32_e32 v165, 0xffff0000, v166
	v_lshlrev_b32_e32 v168, 16, v170
	v_and_b32_e32 v169, 0xffff0000, v170
	v_lshlrev_b32_e32 v172, 16, v174
	v_and_b32_e32 v173, 0xffff0000, v174
	v_lshlrev_b32_e32 v176, 16, v178
	v_and_b32_e32 v177, 0xffff0000, v178
	v_pk_add_f32 v[126:127], v[126:127], v[128:129]
	v_pk_add_f32 v[128:129], v[144:145], v[146:147]
	v_pk_add_f32 v[60:61], v[60:61], v[136:137]
	v_pk_add_f32 v[122:123], v[122:123], v[152:153]
	v_pk_add_f32 v[136:137], v[160:161], v[196:197]
	v_pk_add_f32 v[144:145], v[198:199], v[200:201]
	v_pk_add_f32 v[62:63], v[62:63], v[138:139]
	v_pk_add_f32 v[124:125], v[124:125], v[154:155]
	v_pk_add_f32 v[138:139], v[202:203], v[204:205]
	v_pk_add_f32 v[146:147], v[206:207], v[208:209]
	v_pk_add_f32 v[132:133], v[132:133], v[140:141]
	v_pk_add_f32 v[140:141], v[148:149], v[156:157]
	v_pk_add_f32 v[148:149], v[210:211], v[212:213]
	v_pk_add_f32 v[152:153], v[214:215], v[216:217]
	v_pk_add_f32 v[134:135], v[134:135], v[142:143]
	v_pk_add_f32 v[142:143], v[150:151], v[158:159]
	v_lshlrev_b32_e32 v150, 16, v180
	v_and_b32_e32 v151, 0xffff0000, v180
	v_lshlrev_b32_e32 v154, 16, v184
	v_and_b32_e32 v155, 0xffff0000, v184
	v_lshlrev_b32_e32 v156, 16, v188
	v_and_b32_e32 v157, 0xffff0000, v188
	v_lshlrev_b32_e32 v158, 16, v192
	v_and_b32_e32 v159, 0xffff0000, v192
	v_lshlrev_b32_e32 v202, 16, v34
	v_and_b32_e32 v203, 0xffff0000, v34
	v_lshlrev_b32_e32 v204, 16, v38
	v_and_b32_e32 v205, 0xffff0000, v38
	v_lshlrev_b32_e32 v206, 16, v42
	v_and_b32_e32 v207, 0xffff0000, v42
	v_lshlrev_b32_e32 v208, 16, v46
	v_and_b32_e32 v209, 0xffff0000, v46
	v_lshlrev_b32_e32 v214, 16, v43
	v_and_b32_e32 v215, 0xffff0000, v43
	v_lshlrev_b32_e32 v218, 16, v36
	v_and_b32_e32 v219, 0xffff0000, v36
	v_lshlrev_b32_e32 v220, 16, v40
	v_and_b32_e32 v221, 0xffff0000, v40
	v_lshlrev_b32_e32 v222, 16, v44
	v_and_b32_e32 v223, 0xffff0000, v44
	v_lshlrev_b32_e32 v224, 16, v48
	v_and_b32_e32 v225, 0xffff0000, v48
	v_pk_add_f32 v[42:43], v[10:11], v[12:13]
	v_lshlrev_b32_e32 v166, 16, v167
	v_and_b32_e32 v167, 0xffff0000, v167
	v_lshlrev_b32_e32 v170, 16, v171
	v_and_b32_e32 v171, 0xffff0000, v171
	v_lshlrev_b32_e32 v174, 16, v175
	v_and_b32_e32 v175, 0xffff0000, v175
	v_lshlrev_b32_e32 v178, 16, v179
	v_and_b32_e32 v179, 0xffff0000, v179
	v_lshlrev_b32_e32 v160, 16, v181
	v_and_b32_e32 v161, 0xffff0000, v181
	v_lshlrev_b32_e32 v180, 16, v185
	v_and_b32_e32 v181, 0xffff0000, v185
	v_lshlrev_b32_e32 v184, 16, v189
	v_and_b32_e32 v185, 0xffff0000, v189
	v_lshlrev_b32_e32 v188, 16, v193
	v_and_b32_e32 v189, 0xffff0000, v193
	v_lshlrev_b32_e32 v192, 16, v182
	v_and_b32_e32 v193, 0xffff0000, v182
	v_lshlrev_b32_e32 v196, 16, v186
	v_and_b32_e32 v197, 0xffff0000, v186
	v_lshlrev_b32_e32 v198, 16, v190
	v_and_b32_e32 v199, 0xffff0000, v190
	v_lshlrev_b32_e32 v200, 16, v194
	v_and_b32_e32 v201, 0xffff0000, v194
	v_lshlrev_b32_e32 v210, 16, v35
	v_and_b32_e32 v211, 0xffff0000, v35
	v_lshlrev_b32_e32 v212, 16, v39
	v_and_b32_e32 v213, 0xffff0000, v39
	v_lshlrev_b32_e32 v216, 16, v47
	v_and_b32_e32 v217, 0xffff0000, v47
	v_lshlrev_b32_e32 v230, 16, v45
	v_and_b32_e32 v231, 0xffff0000, v45
	v_lshlrev_b32_e32 v232, 16, v49
	v_and_b32_e32 v233, 0xffff0000, v49
	v_pk_add_f32 v[44:45], v[14:15], v[16:17]
	v_pk_add_f32 v[46:47], v[18:19], v[20:21]
	v_pk_add_f32 v[48:49], v[22:23], v[24:25]
	v_pk_add_f32 v[10:11], v[26:27], v[28:29]
	v_pk_add_f32 v[12:13], v[30:31], v[32:33]
	v_pk_add_f32 v[14:15], v[56:57], v[58:59]
	v_pk_add_f32 v[16:17], v[118:119], v[120:121]
	v_pk_add_f32 v[26:27], v[164:165], v[168:169]
	v_pk_add_f32 v[28:29], v[172:173], v[176:177]
	v_pk_add_f32 v[34:35], v[126:127], v[128:129]
	v_pk_add_f32 v[38:39], v[136:137], v[144:145]
	v_pk_add_f32 v[18:19], v[138:139], v[146:147]
	v_pk_add_f32 v[22:23], v[148:149], v[152:153]
	v_pk_add_f32 v[118:119], v[150:151], v[154:155]
	v_pk_add_f32 v[120:121], v[156:157], v[158:159]
	v_pk_add_f32 v[136:137], v[202:203], v[204:205]
	v_pk_add_f32 v[138:139], v[206:207], v[208:209]
	v_pk_add_f32 v[144:145], v[218:219], v[220:221]
	v_pk_add_f32 v[146:147], v[222:223], v[224:225]
	v_pk_mul_f32 v[152:153], v[42:43], v[42:43]
	v_lshlrev_b32_e32 v226, 16, v37
	v_and_b32_e32 v227, 0xffff0000, v37
	v_lshlrev_b32_e32 v228, 16, v41
	v_and_b32_e32 v229, 0xffff0000, v41
	v_pk_add_f32 v[30:31], v[166:167], v[170:171]
	v_pk_add_f32 v[32:33], v[174:175], v[178:179]
	v_pk_add_f32 v[36:37], v[60:61], v[122:123]
	v_pk_add_f32 v[40:41], v[62:63], v[124:125]
	v_pk_add_f32 v[20:21], v[132:133], v[140:141]
	v_pk_add_f32 v[24:25], v[134:135], v[142:143]
	v_pk_add_f32 v[122:123], v[160:161], v[180:181]
	v_pk_add_f32 v[124:125], v[184:185], v[188:189]
	v_pk_add_f32 v[126:127], v[192:193], v[196:197]
	v_pk_add_f32 v[128:129], v[198:199], v[200:201]
	v_pk_add_f32 v[140:141], v[210:211], v[212:213]
	v_pk_add_f32 v[142:143], v[214:215], v[216:217]
	v_pk_mul_f32 v[154:155], v[44:45], v[44:45]
	v_pk_add_f32 v[56:57], v[10:11], v[12:13]
	v_pk_add_f32 v[58:59], v[14:15], v[16:17]
	v_pk_add_f32 v[60:61], v[26:27], v[28:29]
	v_pk_mul_f32 v[160:161], v[34:35], v[34:35]
	v_pk_mul_f32 v[170:171], v[18:19], v[18:19]
	v_pk_add_f32 v[26:27], v[118:119], v[120:121]
	v_pk_add_f32 v[10:11], v[136:137], v[138:139]
	v_pk_add_f32 v[14:15], v[144:145], v[146:147]
	v_add_f32_e32 v144, v152, v153
	v_pk_add_f32 v[62:63], v[30:31], v[32:33]
	v_pk_mul_f32 v[164:165], v[36:37], v[36:37]
	v_pk_mul_f32 v[172:173], v[20:21], v[20:21]
	v_pk_add_f32 v[28:29], v[122:123], v[124:125]
	v_pk_add_f32 v[30:31], v[126:127], v[128:129]
	v_pk_add_f32 v[12:13], v[140:141], v[142:143]
	v_pk_mul_f32 v[118:119], v[56:57], v[56:57]
	v_add_f32_e32 v145, v160, v161
	v_add_f32_e32 v146, v170, v171
	v_pk_mul_f32 v[126:127], v[26:27], v[26:27]
	v_pk_mul_f32 v[136:137], v[10:11], v[10:11]
	v_add_f32_e32 v144, v154, v144
	v_pk_mul_f32 v[156:157], v[46:47], v[46:47]
	v_pk_mul_f32 v[120:121], v[58:59], v[58:59]
	v_pk_mul_f32 v[128:129], v[28:29], v[28:29]
	v_pk_mul_f32 v[138:139], v[12:13], v[12:13]
	v_add_f32_e32 v118, v118, v119
	v_add_f32_e32 v119, v164, v145
	v_add_f32_e32 v145, v172, v146
	v_add_f32_e32 v126, v126, v127
	v_add_f32_e32 v127, v136, v137
	v_add_f32_e32 v136, v155, v144
	v_lshlrev_b32_e32 v182, 16, v183
	v_and_b32_e32 v183, 0xffff0000, v183
	v_lshlrev_b32_e32 v186, 16, v187
	v_and_b32_e32 v187, 0xffff0000, v187
	v_lshlrev_b32_e32 v190, 16, v191
	v_and_b32_e32 v191, 0xffff0000, v191
	v_lshlrev_b32_e32 v194, 16, v195
	v_and_b32_e32 v195, 0xffff0000, v195
	v_pk_mul_f32 v[166:167], v[38:39], v[38:39]
	v_pk_mul_f32 v[174:175], v[22:23], v[22:23]
	v_add_f32_e32 v118, v120, v118
	v_add_f32_e32 v119, v165, v119
	v_add_f32_e32 v120, v173, v145
	v_add_f32_e32 v126, v128, v126
	v_add_f32_e32 v127, v138, v127
	v_add_f32_e32 v128, v156, v136
	v_pk_add_f32 v[132:133], v[182:183], v[186:187]
	v_pk_add_f32 v[134:135], v[190:191], v[194:195]
	v_pk_mul_f32 v[158:159], v[48:49], v[48:49]
	v_pk_mul_f32 v[122:123], v[60:61], v[60:61]
	v_pk_mul_f32 v[140:141], v[14:15], v[14:15]
	v_add_f32_e32 v118, v121, v118
	v_add_f32_e32 v119, v166, v119
	v_add_f32_e32 v120, v174, v120
	v_add_f32_e32 v121, v129, v126
	v_add_f32_e32 v126, v139, v127
	v_add_f32_e32 v127, v157, v128
	v_pk_add_f32 v[148:149], v[226:227], v[228:229]
	v_pk_add_f32 v[150:151], v[230:231], v[232:233]
	v_pk_mul_f32 v[168:169], v[40:41], v[40:41]
	v_pk_mul_f32 v[176:177], v[24:25], v[24:25]
	v_pk_add_f32 v[32:33], v[132:133], v[134:135]
	v_pk_mul_f32 v[132:133], v[30:31], v[30:31]
	v_add_f32_e32 v118, v122, v118
	v_add_f32_e32 v119, v167, v119
	v_add_f32_e32 v120, v175, v120
	v_add_f32_e32 v122, v140, v126
	v_add_f32_e32 v126, v158, v127
	v_pk_add_f32 v[16:17], v[148:149], v[150:151]
	v_pk_mul_f32 v[124:125], v[62:63], v[62:63]
	v_add_f32_e32 v121, v132, v121
	v_add_f32_e32 v118, v123, v118
	v_add_f32_e32 v119, v168, v119
	v_add_f32_e32 v120, v176, v120
	v_add_f32_e32 v123, v159, v126
	v_pk_mul_f32 v[134:135], v[32:33], v[32:33]
	v_pk_mul_f32 v[142:143], v[16:17], v[16:17]
	v_add_f32_e32 v121, v133, v121
	v_add_f32_e32 v122, v141, v122
	v_add_f32_e32 v118, v124, v118
	v_add_f32_e32 v119, v169, v119
	v_add_f32_e32 v120, v177, v120
	ds_bpermute_b32 v124, v1, v123
	v_add_f32_e32 v121, v134, v121
	v_add_f32_e32 v122, v142, v122
	v_add_f32_e32 v118, v125, v118
	ds_bpermute_b32 v125, v1, v119
	ds_bpermute_b32 v126, v1, v120
	v_add_f32_e32 v121, v135, v121
	v_add_f32_e32 v122, v143, v122
	ds_bpermute_b32 v127, v1, v118
	ds_bpermute_b32 v128, v1, v121
	ds_bpermute_b32 v129, v1, v122
	s_waitcnt lgkmcnt(5)
	v_add_f32_e32 v123, v123, v124
	s_waitcnt lgkmcnt(4)
	v_add_f32_e32 v119, v119, v125
	s_waitcnt lgkmcnt(3)
	v_add_f32_e32 v120, v120, v126
	ds_bpermute_b32 v124, v51, v123
	s_waitcnt lgkmcnt(3)
	v_add_f32_e32 v118, v118, v127
	ds_bpermute_b32 v125, v51, v119
	ds_bpermute_b32 v126, v51, v120
	s_waitcnt lgkmcnt(4)
	v_add_f32_e32 v121, v121, v128
	s_waitcnt lgkmcnt(3)
	v_add_f32_e32 v122, v122, v129
	ds_bpermute_b32 v127, v51, v118
	ds_bpermute_b32 v128, v51, v121
	ds_bpermute_b32 v129, v51, v122
	s_waitcnt lgkmcnt(5)
	v_add_f32_e32 v123, v123, v124
	s_waitcnt lgkmcnt(4)
	v_add_f32_e32 v119, v119, v125
	s_waitcnt lgkmcnt(3)
	v_add_f32_e32 v120, v120, v126
	ds_bpermute_b32 v124, v64, v123
	s_waitcnt lgkmcnt(3)
	v_add_f32_e32 v118, v118, v127
	ds_bpermute_b32 v125, v64, v119
	ds_bpermute_b32 v126, v64, v120
	s_waitcnt lgkmcnt(4)
	v_add_f32_e32 v121, v121, v128
	s_waitcnt lgkmcnt(3)
	v_add_f32_e32 v122, v122, v129
	ds_bpermute_b32 v127, v64, v118
	ds_bpermute_b32 v128, v64, v121
	ds_bpermute_b32 v129, v64, v122
	s_waitcnt lgkmcnt(5)
	v_add_f32_e32 v123, v123, v124
	s_waitcnt lgkmcnt(4)
	v_add_f32_e32 v119, v119, v125
	s_waitcnt lgkmcnt(3)
	v_add_f32_e32 v120, v120, v126
	ds_bpermute_b32 v124, v65, v123
	s_waitcnt lgkmcnt(3)
	v_add_f32_e32 v118, v118, v127
	ds_bpermute_b32 v125, v65, v119
	ds_bpermute_b32 v126, v65, v120
	s_waitcnt lgkmcnt(4)
	v_add_f32_e32 v121, v121, v128
	s_waitcnt lgkmcnt(3)
	v_add_f32_e32 v122, v122, v129
	ds_bpermute_b32 v127, v65, v118
	ds_bpermute_b32 v128, v65, v121
	ds_bpermute_b32 v129, v65, v122
	s_waitcnt lgkmcnt(5)
	v_add_f32_e32 v123, v123, v124
	s_waitcnt lgkmcnt(4)
	v_add_f32_e32 v119, v119, v125
	s_waitcnt lgkmcnt(3)
	v_add_f32_e32 v120, v120, v126
	ds_bpermute_b32 v124, v66, v123
	s_waitcnt lgkmcnt(3)
	v_add_f32_e32 v118, v118, v127
	ds_bpermute_b32 v125, v66, v119
	ds_bpermute_b32 v126, v66, v120
	s_waitcnt lgkmcnt(4)
	v_add_f32_e32 v121, v121, v128
	s_waitcnt lgkmcnt(3)
	v_add_f32_e32 v122, v122, v129
	ds_bpermute_b32 v127, v66, v118
	ds_bpermute_b32 v128, v66, v121
	ds_bpermute_b32 v129, v66, v122
	s_waitcnt lgkmcnt(5)
	v_add_f32_e32 v123, v123, v124
	s_waitcnt lgkmcnt(4)
	v_add_f32_e32 v119, v119, v125
	s_waitcnt lgkmcnt(3)
	v_add_f32_e32 v120, v120, v126
	ds_bpermute_b32 v124, v67, v123
	s_waitcnt lgkmcnt(3)
	v_add_f32_e32 v118, v118, v127
	ds_bpermute_b32 v125, v67, v119
	ds_bpermute_b32 v126, v67, v120
	s_waitcnt lgkmcnt(4)
	v_add_f32_e32 v121, v121, v128
	s_waitcnt lgkmcnt(3)
	v_add_f32_e32 v122, v122, v129
	ds_bpermute_b32 v127, v67, v118
	ds_bpermute_b32 v128, v67, v121
	ds_bpermute_b32 v129, v67, v122
	s_waitcnt lgkmcnt(5)
	v_add_f32_e32 v123, v123, v124
	s_waitcnt lgkmcnt(4)
	v_add_f32_e32 v119, v119, v125
	s_waitcnt lgkmcnt(3)
	v_add_f32_e32 v120, v120, v126
	v_fmamk_f32 v123, v123, 0x3b000000, v68
	s_waitcnt lgkmcnt(2)
	v_add_f32_e32 v118, v118, v127
	v_fmamk_f32 v119, v119, 0x3b000000, v68
	v_fmamk_f32 v120, v120, 0x3b000000, v68
	v_mul_f32_e32 v124, 0x4f800000, v123
	v_cmp_gt_f32_e64 s[4:5], s36, v123
	s_waitcnt lgkmcnt(1)
	v_add_f32_e32 v121, v121, v128
	s_waitcnt lgkmcnt(0)
	v_add_f32_e32 v122, v122, v129
	v_fmamk_f32 v118, v118, 0x3b000000, v68
	v_mul_f32_e32 v125, 0x4f800000, v119
	v_cmp_gt_f32_e32 vcc, s36, v119
	v_mul_f32_e32 v126, 0x4f800000, v120
	v_cmp_gt_f32_e64 s[0:1], s36, v120
	v_cndmask_b32_e64 v123, v123, v124, s[4:5]
	v_fmamk_f32 v121, v121, 0x3b000000, v68
	v_fmamk_f32 v122, v122, 0x3b000000, v68
	v_mul_f32_e32 v124, 0x4f800000, v118
	v_cmp_gt_f32_e64 s[6:7], s36, v118
	v_cndmask_b32_e32 v119, v119, v125, vcc
	v_cndmask_b32_e64 v120, v120, v126, s[0:1]
	v_sqrt_f32_e32 v127, v123
	v_mul_f32_e32 v125, 0x4f800000, v121
	v_cmp_gt_f32_e64 s[8:9], s36, v121
	v_mul_f32_e32 v126, 0x4f800000, v122
	v_cmp_gt_f32_e64 s[10:11], s36, v122
	v_cndmask_b32_e64 v118, v118, v124, s[6:7]
	v_sqrt_f32_e32 v124, v119
	v_sqrt_f32_e32 v128, v120
	v_cndmask_b32_e64 v121, v121, v125, s[8:9]
	v_cndmask_b32_e64 v122, v122, v126, s[10:11]
	v_sqrt_f32_e32 v125, v118
	v_sqrt_f32_e32 v126, v121
	v_sqrt_f32_e32 v129, v122
	v_add_u32_e32 v132, -1, v127
	v_add_u32_e32 v133, 1, v127
	v_add_u32_e32 v134, -1, v124
	v_add_u32_e32 v136, -1, v128
	v_fma_f32 v138, -v132, v127, v123
	v_add_u32_e32 v135, 1, v124
	v_add_u32_e32 v137, 1, v128
	v_fma_f32 v139, -v133, v127, v123
	v_add_u32_e32 v140, -1, v125
	v_fma_f32 v142, -v134, v124, v119
	v_fma_f32 v144, -v136, v128, v120
	v_cmp_ge_f32_e64 s[12:13], 0, v138
	v_add_u32_e32 v141, 1, v125
	v_fma_f32 v143, -v135, v124, v119
	v_fma_f32 v145, -v137, v128, v120
	v_add_u32_e32 v146, -1, v126
	v_add_u32_e32 v148, -1, v129
	v_cndmask_b32_e64 v127, v127, v132, s[12:13]
	v_fma_f32 v132, -v140, v125, v118
	v_cmp_ge_f32_e64 s[12:13], 0, v142
	v_cmp_ge_f32_e64 s[14:15], 0, v144
	v_cmp_lt_f32_e64 s[16:17], 0, v139
	v_add_u32_e32 v147, 1, v126
	v_add_u32_e32 v149, 1, v129
	v_fma_f32 v138, -v141, v125, v118
	v_cndmask_b32_e64 v124, v124, v134, s[12:13]
	v_cmp_lt_f32_e64 s[12:13], 0, v143
	v_cndmask_b32_e64 v128, v128, v136, s[14:15]
	v_cmp_lt_f32_e64 s[14:15], 0, v145
	v_fma_f32 v134, -v146, v126, v121
	v_fma_f32 v142, -v148, v129, v122
	v_cndmask_b32_e64 v127, v127, v133, s[16:17]
	v_cmp_ge_f32_e64 s[16:17], 0, v132
	v_fma_f32 v136, -v147, v126, v121
	v_fma_f32 v143, -v149, v129, v122
	v_cndmask_b32_e64 v125, v125, v140, s[16:17]
	v_cmp_lt_f32_e64 s[16:17], 0, v138
	v_cndmask_b32_e64 v124, v124, v135, s[12:13]
	v_cndmask_b32_e64 v128, v128, v137, s[14:15]
	v_cmp_ge_f32_e64 s[12:13], 0, v134
	v_cmp_ge_f32_e64 s[14:15], 0, v142
	v_mul_f32_e32 v132, 0x37800000, v127
	v_cndmask_b32_e64 v126, v126, v146, s[12:13]
	v_cmp_lt_f32_e64 s[12:13], 0, v136
	v_cndmask_b32_e64 v129, v129, v148, s[14:15]
	v_cmp_lt_f32_e64 s[14:15], 0, v143
	v_cndmask_b32_e64 v125, v125, v141, s[16:17]
	v_mul_f32_e32 v133, 0x37800000, v124
	v_mul_f32_e32 v134, 0x37800000, v128
	v_cndmask_b32_e64 v126, v126, v147, s[12:13]
	v_cndmask_b32_e64 v129, v129, v149, s[14:15]
	v_cndmask_b32_e64 v127, v127, v132, s[4:5]
	v_mul_f32_e32 v132, 0x37800000, v125
	v_cmp_class_f32_e64 s[4:5], v123, v69
	v_cndmask_b32_e32 v124, v124, v133, vcc
	v_cmp_class_f32_e32 vcc, v119, v69
	v_cndmask_b32_e64 v128, v128, v134, s[0:1]
	v_cmp_class_f32_e64 s[0:1], v120, v69
	v_mul_f32_e32 v133, 0x37800000, v126
	v_mul_f32_e32 v134, 0x37800000, v129
	v_cndmask_b32_e64 v123, v127, v123, s[4:5]
	v_cndmask_b32_e64 v125, v125, v132, s[6:7]
	v_cmp_class_f32_e64 s[4:5], v118, v69
	v_cndmask_b32_e32 v119, v124, v119, vcc
	v_cndmask_b32_e64 v120, v128, v120, s[0:1]
	v_cndmask_b32_e64 v124, v126, v133, s[8:9]
	v_cmp_class_f32_e32 vcc, v121, v69
	v_cndmask_b32_e64 v126, v129, v134, s[10:11]
	v_cmp_class_f32_e64 s[0:1], v122, v69
	v_div_scale_f32 v127, s[6:7], v123, v123, 1.0
	v_cndmask_b32_e64 v125, v125, v118, s[4:5]
	v_div_scale_f32 v118, s[4:5], v119, v119, 1.0
	v_div_scale_f32 v132, s[8:9], v120, v120, 1.0
	v_cndmask_b32_e32 v121, v124, v121, vcc
	v_cndmask_b32_e64 v122, v126, v122, s[0:1]
	v_rcp_f32_e32 v124, v127
	v_div_scale_f32 v126, s[0:1], v125, v125, 1.0
	v_rcp_f32_e32 v135, v118
	v_rcp_f32_e32 v136, v132
	v_div_scale_f32 v137, s[0:1], v121, v121, 1.0
	v_div_scale_f32 v139, s[0:1], v122, v122, 1.0
	v_rcp_f32_e32 v141, v126
	v_rcp_f32_e32 v142, v137
	v_rcp_f32_e32 v143, v139
	v_fma_f32 v144, -v127, v124, 1.0
	v_div_scale_f32 v128, s[6:7], 1.0, v123, 1.0
	v_fma_f32 v145, -v118, v135, 1.0
	v_fma_f32 v146, -v132, v136, 1.0
	v_fmac_f32_e32 v124, v144, v124
	v_fma_f32 v144, -v126, v141, 1.0
	v_div_scale_f32 v129, s[4:5], 1.0, v119, 1.0
	v_div_scale_f32 v134, s[10:11], 1.0, v125, 1.0
	v_fmac_f32_e32 v135, v145, v135
	v_fmac_f32_e32 v136, v146, v136
	v_fma_f32 v145, -v137, v142, 1.0
	v_fma_f32 v146, -v139, v143, 1.0
	v_mul_f32_e32 v147, v128, v124
	v_fmac_f32_e32 v141, v144, v141
	v_mul_f32_e32 v144, v129, v135
	v_fmac_f32_e32 v142, v145, v142
	v_fmac_f32_e32 v143, v146, v143
	v_fma_f32 v145, -v127, v147, v128
	v_mul_f32_e32 v146, v134, v141
	v_div_scale_f32 v133, s[8:9], 1.0, v120, 1.0
	v_fma_f32 v149, -v118, v144, v129
	v_fmac_f32_e32 v147, v145, v124
	v_fma_f32 v145, -v126, v146, v134
	v_div_scale_f32 v138, s[12:13], 1.0, v121, 1.0
	v_mul_f32_e32 v148, v133, v136
	v_fmac_f32_e32 v144, v149, v135
	v_fma_f32 v127, -v127, v147, v128
	v_fmac_f32_e32 v146, v145, v141
	s_mov_b64 vcc, s[6:7]
	v_fma_f32 v150, -v132, v148, v133
	v_mul_f32_e32 v151, v138, v142
	v_fma_f32 v128, -v118, v144, v129
	v_div_fmas_f32 v118, v127, v124, v147
	v_fma_f32 v124, -v126, v146, v134
	s_mov_b64 vcc, s[10:11]
	v_div_scale_f32 v140, s[0:1], 1.0, v122, 1.0
	v_fmac_f32_e32 v148, v150, v136
	v_fma_f32 v149, -v137, v151, v138
	v_div_fixup_f32 v118, v118, v123, 1.0
	v_div_fmas_f32 v123, v124, v141, v146
	s_mov_b64 vcc, s[4:5]
	v_mul_f32_e32 v152, v140, v143
	v_fma_f32 v129, -v132, v148, v133
	v_fmac_f32_e32 v151, v149, v142
	v_pk_mul_f32 v[42:43], v[42:43], v[118:119] op_sel_hi:[1,0]
	v_pk_mul_f32 v[44:45], v[44:45], v[118:119] op_sel_hi:[1,0]
	v_pk_mul_f32 v[46:47], v[46:47], v[118:119] op_sel_hi:[1,0]
	v_pk_mul_f32 v[48:49], v[48:49], v[118:119] op_sel_hi:[1,0]
	v_div_fixup_f32 v118, v123, v125, 1.0
	v_div_fmas_f32 v123, v128, v135, v144
	s_mov_b64 vcc, s[8:9]
	v_fma_f32 v150, -v139, v152, v140
	v_fma_f32 v126, -v137, v151, v138
	v_pk_mul_f32 v[48:49], v[4:5], v[48:49]
	v_pk_mul_f32 v[56:57], v[56:57], v[118:119] op_sel_hi:[1,0]
	v_pk_mul_f32 v[58:59], v[58:59], v[118:119] op_sel_hi:[1,0]
	v_pk_mul_f32 v[60:61], v[60:61], v[118:119] op_sel_hi:[1,0]
	v_pk_mul_f32 v[62:63], v[62:63], v[118:119] op_sel_hi:[1,0]
	v_div_fixup_f32 v118, v123, v119, 1.0
	v_div_fmas_f32 v119, v129, v136, v148
	s_mov_b64 vcc, s[12:13]
	v_fmac_f32_e32 v152, v150, v143
	v_pk_mul_f32 v[44:45], v[8:9], v[44:45]
	v_pk_mul_f32 v[42:43], v[6:7], v[42:43]
	v_pk_mul_f32 v[46:47], v[2:3], v[46:47]
	v_mul_f32_e32 v116, v48, v116
	v_mul_f32_e32 v117, v49, v117
	v_pk_mul_f32 v[48:49], v[2:3], v[60:61]
	v_pk_mul_f32 v[38:39], v[38:39], v[118:119] op_sel_hi:[1,0]
	v_div_fixup_f32 v60, v119, v120, 1.0
	v_div_fmas_f32 v61, v126, v142, v151
	v_fma_f32 v127, -v139, v152, v140
	v_mul_f32_e32 v110, v42, v110
	v_mul_f32_e32 v111, v43, v111
	v_mul_f32_e32 v112, v44, v112
	v_mul_f32_e32 v113, v45, v113
	v_mul_f32_e32 v114, v46, v114
	v_mul_f32_e32 v115, v47, v115
	v_pk_mul_f32 v[42:43], v[8:9], v[58:59]
	v_pk_mul_f32 v[44:45], v[6:7], v[56:57]
	v_pk_mul_f32 v[46:47], v[4:5], v[62:63]
	v_pk_mul_f32 v[56:57], v[34:35], v[118:119] op_sel_hi:[1,0]
	v_pk_mul_f32 v[58:59], v[36:37], v[118:119] op_sel_hi:[1,0]
	v_pk_mul_f32 v[40:41], v[40:41], v[118:119] op_sel_hi:[1,0]
	v_pk_mul_f32 v[38:39], v[2:3], v[38:39]
	v_pk_mul_f32 v[22:23], v[22:23], v[60:61] op_sel_hi:[1,0]
	s_mov_b64 vcc, s[0:1]
	v_cvt_pk_bf16_f32 v34, v110, v111
	v_cvt_pk_bf16_f32 v35, v112, v113
	v_cvt_pk_bf16_f32 v36, v114, v115
	v_cvt_pk_bf16_f32 v37, v116, v117
	v_mul_f32_e32 v62, v44, v102
	v_mul_f32_e32 v63, v45, v103
	v_mul_f32_e32 v102, v42, v104
	v_mul_f32_e32 v103, v43, v105
	v_mul_f32_e32 v104, v48, v106
	v_mul_f32_e32 v105, v49, v107
	v_mul_f32_e32 v106, v46, v108
	v_mul_f32_e32 v107, v47, v109
	v_pk_mul_f32 v[42:43], v[8:9], v[58:59]
	v_pk_mul_f32 v[44:45], v[6:7], v[56:57]
	v_pk_mul_f32 v[40:41], v[4:5], v[40:41]
	v_pk_mul_f32 v[46:47], v[18:19], v[60:61] op_sel_hi:[1,0]
	v_pk_mul_f32 v[48:49], v[20:21], v[60:61] op_sel_hi:[1,0]
	v_pk_mul_f32 v[24:25], v[24:25], v[60:61] op_sel_hi:[1,0]
	v_div_fixup_f32 v56, v61, v121, 1.0
	v_div_fmas_f32 v57, v127, v143, v152
	global_store_dwordx4 v130, v[34:37], s[28:29]
	v_cvt_pk_bf16_f32 v18, v62, v63
	v_cvt_pk_bf16_f32 v19, v102, v103
	v_cvt_pk_bf16_f32 v20, v104, v105
	v_mul_f32_e32 v39, v39, v99
	v_pk_mul_f32 v[22:23], v[2:3], v[22:23]
	v_cvt_pk_bf16_f32 v21, v106, v107
	v_mul_f32_e32 v44, v44, v94
	v_mul_f32_e32 v45, v45, v95
	v_mul_f32_e32 v42, v42, v96
	v_mul_f32_e32 v43, v43, v97
	v_mul_f32_e32 v58, v38, v98
	v_mul_f32_e32 v40, v40, v100
	v_mul_f32_e32 v41, v41, v101
	v_pk_mul_f32 v[34:35], v[8:9], v[48:49]
	v_pk_mul_f32 v[36:37], v[6:7], v[46:47]
	v_pk_mul_f32 v[24:25], v[4:5], v[24:25]
	v_pk_mul_f32 v[26:27], v[26:27], v[56:57] op_sel_hi:[1,0]
	v_pk_mul_f32 v[28:29], v[28:29], v[56:57] op_sel_hi:[1,0]
	v_pk_mul_f32 v[30:31], v[30:31], v[56:57] op_sel_hi:[1,0]
	v_pk_mul_f32 v[32:33], v[32:33], v[56:57] op_sel_hi:[1,0]
	v_div_fixup_f32 v38, v57, v122, 1.0
	global_store_dwordx4 v130, v[18:21], s[28:29] offset:1024
	v_mul_f32_e32 v36, v36, v86
	v_mul_f32_e32 v37, v37, v87
	v_cvt_pk_bf16_f32 v18, v44, v45
	v_cvt_pk_bf16_f32 v19, v42, v43
	v_cvt_pk_bf16_f32 v20, v58, v39
	v_mul_f32_e32 v39, v22, v90
	v_cvt_pk_bf16_f32 v21, v40, v41
	v_mul_f32_e32 v34, v34, v88
	v_mul_f32_e32 v35, v35, v89
	v_mul_f32_e32 v40, v23, v91
	v_mul_f32_e32 v41, v24, v92
	v_mul_f32_e32 v42, v25, v93
	v_pk_mul_f32 v[22:23], v[8:9], v[28:29]
	v_pk_mul_f32 v[24:25], v[6:7], v[26:27]
	v_pk_mul_f32 v[26:27], v[4:5], v[32:33]
	v_pk_mul_f32 v[28:29], v[2:3], v[30:31]
	v_pk_mul_f32 v[30:31], v[10:11], v[38:39] op_sel_hi:[1,0]
	v_pk_mul_f32 v[32:33], v[12:13], v[38:39] op_sel_hi:[1,0]
	v_pk_mul_f32 v[14:15], v[14:15], v[38:39] op_sel_hi:[1,0]
	v_pk_mul_f32 v[16:17], v[16:17], v[38:39] op_sel_hi:[1,0]
	global_store_dwordx4 v130, v[18:21], s[28:29] offset:2048
	v_cvt_pk_bf16_f32 v10, v36, v37
	v_cvt_pk_bf16_f32 v11, v34, v35
	v_cvt_pk_bf16_f32 v12, v39, v40
	v_cvt_pk_bf16_f32 v13, v41, v42
	v_mul_f32_e32 v24, v24, v78
	v_mul_f32_e32 v25, v25, v79
	v_mul_f32_e32 v22, v22, v80
	v_mul_f32_e32 v23, v23, v81
	v_mul_f32_e32 v28, v28, v82
	v_mul_f32_e32 v29, v29, v83
	v_mul_f32_e32 v26, v26, v84
	v_mul_f32_e32 v27, v27, v85
	v_pk_mul_f32 v[18:19], v[8:9], v[32:33]
	v_pk_mul_f32 v[20:21], v[6:7], v[30:31]
	v_pk_mul_f32 v[16:17], v[4:5], v[16:17]
	v_pk_mul_f32 v[14:15], v[2:3], v[14:15]
	global_store_dwordx4 v130, v[10:13], s[28:29] offset:3072
	v_mul_f32_e32 v20, v20, v70
	v_mul_f32_e32 v21, v21, v71
	v_cvt_pk_bf16_f32 v10, v24, v25
	v_cvt_pk_bf16_f32 v11, v22, v23
	v_cvt_pk_bf16_f32 v12, v28, v29
	v_cvt_pk_bf16_f32 v13, v26, v27
	v_mul_f32_e32 v18, v18, v72
	v_mul_f32_e32 v19, v19, v73
	v_mul_f32_e32 v14, v14, v74
	v_mul_f32_e32 v15, v15, v75
	v_mul_f32_e32 v16, v16, v76
	v_mul_f32_e32 v17, v17, v77
	global_store_dwordx4 v[54:55], v[10:13], off
	s_nop 1
	v_cvt_pk_bf16_f32 v10, v20, v21
	v_cvt_pk_bf16_f32 v11, v18, v19
	v_cvt_pk_bf16_f32 v12, v14, v15
	v_cvt_pk_bf16_f32 v13, v16, v17
	global_store_dwordx4 v[54:55], v[10:13], off offset:1024
	s_cbranch_scc1 .LBB0_1595
	s_cmpk_eq_u32 s99, 0x7771
	s_cbranch_scc0 .LBB0_1596
	s_movk_i32 s99, 0x7772
	v_writelane_b32 v254, s16, 27
	v_writelane_b32 v254, s21, 28
	v_writelane_b32 v254, s23, 29
	s_waitcnt vmcnt(0) lgkmcnt(0)
	s_barrier
	s_branch .Le22_gemm
